# SWA: last (causal-edge) key tile bias add batched as well (16 ds_read_b32, one wait, add + cndmask with the precomputed lane masks)
# speedup vs baseline: 1.0026x; 1.0021x over previous
; __device__ __forceinline__ float xhalf_max(float x) { float a, b; xhalf_swap(x, a, b); float m; asm("v_max3_f32 %0, %1, %2, %3" : "=v"(m) : "v"(x), "v"(a), "v"(b)); return m; }
; __device__ __forceinline__ void swa_unit(LAS unsigned char* lds, const bf16_t* Z1, const bf16_t* VTA, const float* bias2, const float* sinks, bf16_t* OA, int b, int kvh, int qblk, int wv) {
;     ...
;             const float mx = xhalf_max(max16(sc));
;             float alpha = 1.0f;
;             if (__any(mx > m + RESCALE_THR)) {
;                 const float mn = fmaxf(m, mx); alpha = __builtin_amdgcn_exp2f(m - mn); m = mn;
; #pragma unroll
;                 for (int i = 0; i < 16; ++i) { o0[i] *= alpha; o1[i] *= alpha; }
;             }
.Lswa_endk4:
	v_max3_f32 v0, v51, v50, v35
	v_max3_f32 v48, v34, v37, v36
	v_max3_f32 v49, v39, v38, v41
	v_max3_f32 v52, v40, v43, v42
	v_max3_f32 v53, v45, v44, v47
	s_nop 0
	v_max3_f32 v0, v0, v48, v49
	v_max3_f32 v48, v52, v53, v46
	s_nop 0
	v_max3_f32 v0, v0, v48, v46
	s_nop 0
	v_mov_b32_e32 v48, v0
	v_mov_b32_e32 v49, v0
	s_nop 1
	v_permlane32_swap_b32 v48, v49
	s_nop 1
	s_nop 0
	v_max3_f32 v0, v0, v48, v49
	v_add_f32_e32 v48, 0x40c00000, v128
	v_cmp_gt_f32_e32 vcc, v0, v48
	s_cbranch_vccz .LBB0_793
	v_max_f32_e32 v0, v0, v0
	v_max_f32_e32 v48, v128, v128
	v_max_f32_e32 v48, v48, v0
	v_sub_f32_e32 v0, v128, v48
	v_exp_f32_e32 v0, v0
	v_mov_b32_e32 v128, v48
	v_pk_mul_f32 v[32:33], v[32:33], v[0:1] op_sel_hi:[1,0]
	v_pk_mul_f32 v[30:31], v[30:31], v[0:1] op_sel_hi:[1,0]
	v_pk_mul_f32 v[28:29], v[28:29], v[0:1] op_sel_hi:[1,0]
	v_pk_mul_f32 v[26:27], v[26:27], v[0:1] op_sel_hi:[1,0]
	v_pk_mul_f32 v[24:25], v[24:25], v[0:1] op_sel_hi:[1,0]
	v_pk_mul_f32 v[22:23], v[22:23], v[0:1] op_sel_hi:[1,0]
	v_pk_mul_f32 v[20:21], v[20:21], v[0:1] op_sel_hi:[1,0]
	v_pk_mul_f32 v[18:19], v[18:19], v[0:1] op_sel_hi:[1,0]
	v_pk_mul_f32 v[16:17], v[16:17], v[0:1] op_sel_hi:[1,0]
	v_pk_mul_f32 v[14:15], v[14:15], v[0:1] op_sel_hi:[1,0]
	v_pk_mul_f32 v[12:13], v[12:13], v[0:1] op_sel_hi:[1,0]
	v_pk_mul_f32 v[10:11], v[10:11], v[0:1] op_sel_hi:[1,0]
	v_pk_mul_f32 v[8:9], v[8:9], v[0:1] op_sel_hi:[1,0]
	v_pk_mul_f32 v[6:7], v[6:7], v[0:1] op_sel_hi:[1,0]
	v_pk_mul_f32 v[4:5], v[4:5], v[0:1] op_sel_hi:[1,0]
	v_pk_mul_f32 v[2:3], v[2:3], v[0:1] op_sel_hi:[1,0]

; #define LAS __attribute__((address_space(3)))
; #define MFMA32(a, b, c) __builtin_amdgcn_mfma_f32_32x32x16_bf16((a), (b), (c), 0, 0, 0)
; __device__ __forceinline__ int crow(int i, int hh) { return (i & 3) + 8 * (i >> 2) + 4 * hh; }
; __device__ __forceinline__ void swa_unit(LAS unsigned char* lds, const bf16_t* Z1, const bf16_t* VTA, const float* bias2, const float* sinks, bf16_t* OA, int b, int kvh, int qblk, int wv) {
;     ...
;         for (int kt = 0; kt < 5; ++kt) {
;             const int kb = q0w + 32 * kt;
;             if (Q0 == 0 && kb + 31 < 128) continue;
;             f32x16 sc;
; #pragma unroll
;             for (int i = 0; i < 16; ++i) sc[i] = 0.f;
; #pragma unroll
;             for (int s = 0; s < 4; ++s) { const bf16x8 a = *(const LAS bf16x8*)(lds + (kb + r) * SK_ROW + s * 32 + hh * 16); sc = MFMA32(a, qf[s], sc); }
; #pragma unroll
;             for (int i = 0; i < 16; ++i) { const int c = crow(i, hh), dist = 128 - 32 * kt + r - c;
;                 const bool ok = (dist >= 0) && (dist < 128) && (Q0 > 0 || kb + c >= 128);
;                 sc[i] = ok ? sc[i] + bl[dist & 127] : -INFINITY; }
.LBB0_870:
	s_add_i32 s25, s30, 0x80
	s_or_b32 s16, s25, 31
	s_cmpk_lt_i32 s16, 0x80
	s_cselect_b64 s[16:17], -1, 0
	s_and_b64 s[16:17], s[8:9], s[16:17]
	s_and_b64 vcc, exec, s[16:17]
	s_cbranch_vccnz .LBB0_690
	v_or_b32_e32 v0, s25, v71
	v_mad_u64_u32 v[130:131], s[16:17], v0, s19, v[70:71]
	ds_read_b128 v[34:37], v130
	v_or_b32_e32 v0, s25, v78
	s_waitcnt vmcnt(3) lgkmcnt(0)
	v_mfma_f32_32x32x16_bf16 v[34:49], v[34:37], v[62:65], 0
	ds_read_b128 v[62:65], v130 offset:32
	s_waitcnt vmcnt(2) lgkmcnt(0)
	v_mfma_f32_32x32x16_bf16 v[34:49], v[62:65], v[58:61], v[34:49]
	ds_read_b128 v[58:61], v130 offset:64
	s_waitcnt vmcnt(1) lgkmcnt(0)
	v_mfma_f32_32x32x16_bf16 v[34:49], v[58:61], v[54:57], v[34:49]
	ds_read_b128 v[54:57], v130 offset:96
	s_waitcnt vmcnt(0) lgkmcnt(0)
	v_mfma_f32_32x32x16_bf16 v[34:49], v[54:57], v[50:53], v[34:49]
	v_mov_b32_e32 v50, 0xff800000
	v_mov_b32_e32 v51, 0xff800000
	s_cmp_eq_u64 s[10:11], -1
	s_cbranch_scc1 .Lswa_fastk4
	s_and_saveexec_b64 s[16:17], s[68:69]
	s_cbranch_execz .LBB0_875
	v_cmp_lt_i32_e32 vcc, s3, v0
	s_or_b64 s[22:23], s[10:11], vcc
	v_mov_b32_e32 v51, 0xff800000
	s_and_saveexec_b64 s[30:31], s[22:23]
	s_cbranch_execz .LBB0_874
	ds_read_b32 v51, v80
	s_waitcnt lgkmcnt(0)
	s_nop 0
	v_add_f32_e32 v51, v34, v51

; __device__ __forceinline__ int crow(int i, int hh) { return (i & 3) + 8 * (i >> 2) + 4 * hh; }
; __device__ __forceinline__ void swa_unit(LAS unsigned char* lds, const bf16_t* Z1, const bf16_t* VTA, const float* bias2, const float* sinks, bf16_t* OA, int b, int kvh, int qblk, int wv) {
;     ...
;             for (int i = 0; i < 16; ++i) { const int c = crow(i, hh), dist = 128 - 32 * kt + r - c;
;                 const bool ok = (dist >= 0) && (dist < 128) && (Q0 > 0 || kb + c >= 128);
;                 sc[i] = ok ? sc[i] + bl[dist & 127] : -INFINITY; }
.Lswa_fastk4:
	ds_read_b32 v144, v80
	ds_read_b32 v145, v112 offset:512
	ds_read_b32 v146, v113 offset:512
	ds_read_b32 v147, v114 offset:512
	ds_read_b32 v148, v115 offset:512
	ds_read_b32 v149, v116 offset:512
	ds_read_b32 v150, v117 offset:512
	ds_read_b32 v151, v118 offset:512
	ds_read_b32 v152, v119 offset:512
	ds_read_b32 v153, v120 offset:512
	ds_read_b32 v154, v121 offset:512
	ds_read_b32 v155, v122 offset:512
	ds_read_b32 v156, v123 offset:512
	ds_read_b32 v157, v124 offset:512
	ds_read_b32 v158, v125 offset:512
	ds_read_b32 v159, v126 offset:512
	v_mov_b32_e32 v160, 0xff800000
	s_waitcnt lgkmcnt(0)
	v_add_f32_e32 v144, v34, v144
	v_cndmask_b32_e64 v51, v160, v144, s[68:69]
	v_add_f32_e32 v145, v35, v145
	v_cndmask_b32_e64 v50, v160, v145, s[70:71]
	v_add_f32_e32 v146, v36, v146
	v_cndmask_b32_e64 v35, v160, v146, s[72:73]
	v_add_f32_e32 v147, v37, v147
	v_cndmask_b32_e64 v34, v160, v147, s[74:75]
	v_add_f32_e32 v148, v38, v148
	v_cndmask_b32_e64 v37, v160, v148, s[76:77]
	v_add_f32_e32 v149, v39, v149
	v_cndmask_b32_e64 v36, v160, v149, s[78:79]
	v_add_f32_e32 v150, v40, v150
	v_cndmask_b32_e64 v39, v160, v150, s[80:81]
	v_add_f32_e32 v151, v41, v151
	v_cndmask_b32_e64 v38, v160, v151, s[82:83]
	v_add_f32_e32 v152, v42, v152
	v_cndmask_b32_e64 v41, v160, v152, s[84:85]
	v_add_f32_e32 v153, v43, v153
	v_cndmask_b32_e64 v40, v160, v153, s[86:87]
	v_add_f32_e32 v154, v44, v154
	v_cndmask_b32_e64 v43, v160, v154, s[88:89]
	v_add_f32_e32 v155, v45, v155
	v_cndmask_b32_e64 v42, v160, v155, s[90:91]
	v_add_f32_e32 v156, v46, v156
	v_cndmask_b32_e64 v45, v160, v156, s[92:93]
	v_add_f32_e32 v157, v47, v157
	v_cndmask_b32_e64 v44, v160, v157, s[94:95]
	v_add_f32_e32 v158, v48, v158
	v_cndmask_b32_e64 v47, v160, v158, s[96:97]
	v_add_f32_e32 v159, v49, v159
	v_cndmask_b32_e64 v46, v160, v159, s[0:1]
	s_branch .Lswa_endk4
